# phase 0: hand-written W1 transposes (8x dwordx4 loads in flight per item)
# baseline (speedup 1.0000x reference)
; #define LAS __attribute__((address_space(3)))
; __device__ __forceinline__ unsigned pk2(float lo, float hi) { f32x2 v = {lo, hi}; bf16x2_t b = __builtin_convertvector(v, bf16x2_t); return __builtin_bit_cast(unsigned, b); }
;     __device__ __forceinline__ const float* in(int i) const { return (const float*)ptr(i); }
;     __device__ __forceinline__ unsigned char* ws() const { return (unsigned char*)ptr(37); }
; #define ws (p.ws())
; __device__ __forceinline__ void transpose_item(const float* W, int K, int N, bf16_t* WT, int k0, int n0, int drow0, LAS float* scr, int lane) {
; #pragma unroll 8
;     for (int i = 0; i < 32; ++i) { const int kk = 2 * i + (lane >> 5); scr[kk * 33 + (lane & 31)] = W[(size_t)(k0 + kk) * N + n0 + (lane & 31)]; }
;     asm volatile("s_waitcnt lgkmcnt(0)" ::: "memory");
;     const int c = lane & 7;
; #pragma unroll
;     for (int j = 0; j < 4; ++j) { const int n = (lane >> 3) + 8 * j; const LAS float* s = scr + (8 * c) * 33 + n;
;         u32x4 o; o.x = pk2(s[0 * 33], s[1 * 33]); o.y = pk2(s[2 * 33], s[3 * 33]); o.z = pk2(s[4 * 33], s[5 * 33]); o.w = pk2(s[6 * 33], s[7 * 33]);
;         *(u32x4*)(WT + (size_t)(drow0 + n) * K + k0 + 8 * c) = o; }
;     asm volatile("s_waitcnt lgkmcnt(0)" ::: "memory");
; }
; __device__ __forceinline__ void phase_prologue(const Ctx& p, LAS unsigned char* lds) {
;     ...
;     constexpr int I1 = 16 * 176;
;     for (int it = gw; it < I1; it += NGW) { const int kb = it / 176, nb = it % 176; transpose_item(p.in(7), DM, NFF, (bf16_t*)(ws + WS_W1T), 64 * kb, 32 * nb, map_w1(32 * nb), scr, lane); }
.LBB0_15:
	s_or_b64 exec, exec, s[2:3]
	s_cmp_lt_i32 s36, 1
	s_cselect_b64 s[2:3], -1, 0
	s_cmp_gt_i32 s37, 0
	s_cselect_b64 s[6:7], -1, 0
	s_and_b64 s[6:7], s[2:3], s[6:7]
	s_andn2_b64 vcc, exec, s[6:7]
	s_cbranch_vccnz .LBB0_66
	s_add_i32 s3, 0, 0x23528
	v_mov_b32_e32 v1, s3
	ds_read_b64 v[2:3], v1
	v_readfirstlane_b32 s2, v180
	s_lshr_b32 s2, s2, 6
	s_lshl_b32 s3, s28, 3
	s_add_i32 s10, s2, s3
	s_lshl_b32 s8, s38, 3
	v_and_b32_e32 v34, 63, v180
	s_waitcnt lgkmcnt(0)
	v_readfirstlane_b32 s12, v2
	s_cmpk_gt_i32 s10, 0xaff
	v_readfirstlane_b32 s13, v3
	s_cbranch_scc1 .LBB0_25
	v_mov_b32_e32 v0, 0x23438
	ds_read_b64 v[4:5], v0
	v_readfirstlane_b32 s2, v180
	s_waitcnt lgkmcnt(0)
	v_readfirstlane_b32 s40, v4
	v_readfirstlane_b32 s41, v5
	s_nop 4
	s_lshr_b32 s45, s2, 6
	s_mov_b32 s44, s10
	s_lshl_b32 s3, s45, 14
	v_lshrrev_b32_e32 v1, 3, v34
	v_and_b32_e32 v2, 7, v34
	v_mul_u32_u24_e32 v14, 0x84, v1
	v_lshl_add_u32 v14, v2, 4, v14
	v_add_u32_e32 v14, s3, v14
	v_mul_u32_u24_e32 v15, 0x420, v2
	v_lshl_add_u32 v15, v1, 2, v15
	v_add_u32_e32 v15, s3, v15
	v_mul_u32_u24_e32 v13, 0x5800, v1
	v_lshl_add_u32 v13, v2, 4, v13
	v_lshlrev_b32_e32 v4, 11, v1
	v_lshl_add_u32 v4, v2, 4, v4
	v_add_u32_e32 v5, 0x4000, v4
	v_add_u32_e32 v6, 0x8000, v4
	v_add_u32_e32 v7, 0xc000, v4
.Lw1_item:
	s_cmpk_gt_u32 s44, 0xaff
	s_cbranch_scc1 .LBB0_25
	s_mul_hi_u32 s4, s44, 0x1745d18
	s_mul_i32 s5, s4, 0xb0
	s_sub_u32 s5, s44, s5
	s_mul_i32 s22, s4, 0x160000
	s_lshl_b32 s23, s5, 7
	s_add_u32 s22, s22, s23
	s_add_u32 s14, s40, s22
	s_addc_u32 s15, s41, 0
	s_cmpk_lt_u32 s5, 0x58
	s_cselect_b32 s20, 0, 0x80
	s_cselect_b32 s21, 0, 0x58
	s_sub_u32 s5, s5, s21
	s_lshr_b32 s21, s5, 2
	s_lshl_b32 s21, s21, 8
	s_and_b32 s5, s5, 3
	s_lshl_b32 s5, s5, 5
	s_add_u32 s21, s21, s5
	s_add_u32 s21, s21, s20
	s_lshl_b32 s21, s21, 11
	s_lshl_b32 s4, s4, 7
	s_add_u32 s21, s21, s4
	s_add_u32 s16, s12, s21
	s_addc_u32 s17, s13, 0
	global_load_dwordx4 v[48:51], v13, s[14:15]
	v_add_u32_e32 v12, 0x2c000, v13
	global_load_dwordx4 v[52:55], v12, s[14:15]
	v_add_u32_e32 v12, 0x2c000, v12
	global_load_dwordx4 v[56:59], v12, s[14:15]
	v_add_u32_e32 v12, 0x2c000, v12
	global_load_dwordx4 v[60:63], v12, s[14:15]
	v_add_u32_e32 v12, 0x2c000, v12
	global_load_dwordx4 v[64:67], v12, s[14:15]
	v_add_u32_e32 v12, 0x2c000, v12
	global_load_dwordx4 v[68:71], v12, s[14:15]
	v_add_u32_e32 v12, 0x2c000, v12
	global_load_dwordx4 v[72:75], v12, s[14:15]
	v_add_u32_e32 v12, 0x2c000, v12
	global_load_dwordx4 v[76:79], v12, s[14:15]
	s_waitcnt vmcnt(7)
	ds_write_b32 v14, v48 offset:0
	ds_write_b32 v14, v49 offset:4
	ds_write_b32 v14, v50 offset:8
	ds_write_b32 v14, v51 offset:12
	s_waitcnt vmcnt(6)
	ds_write_b32 v14, v52 offset:1056
	ds_write_b32 v14, v53 offset:1060
	ds_write_b32 v14, v54 offset:1064
	ds_write_b32 v14, v55 offset:1068
	s_waitcnt vmcnt(5)
	ds_write_b32 v14, v56 offset:2112
	ds_write_b32 v14, v57 offset:2116
	ds_write_b32 v14, v58 offset:2120
	ds_write_b32 v14, v59 offset:2124
	s_waitcnt vmcnt(4)
	ds_write_b32 v14, v60 offset:3168
	ds_write_b32 v14, v61 offset:3172
	ds_write_b32 v14, v62 offset:3176
	ds_write_b32 v14, v63 offset:3180
	s_waitcnt vmcnt(3)
	ds_write_b32 v14, v64 offset:4224
	ds_write_b32 v14, v65 offset:4228
	ds_write_b32 v14, v66 offset:4232
	ds_write_b32 v14, v67 offset:4236
	s_waitcnt vmcnt(2)
	ds_write_b32 v14, v68 offset:5280
	ds_write_b32 v14, v69 offset:5284
	ds_write_b32 v14, v70 offset:5288
	ds_write_b32 v14, v71 offset:5292
	s_waitcnt vmcnt(1)
	ds_write_b32 v14, v72 offset:6336
	ds_write_b32 v14, v73 offset:6340
	ds_write_b32 v14, v74 offset:6344
	ds_write_b32 v14, v75 offset:6348
	s_waitcnt vmcnt(0)
	ds_write_b32 v14, v76 offset:7392
	ds_write_b32 v14, v77 offset:7396
	ds_write_b32 v14, v78 offset:7400
	ds_write_b32 v14, v79 offset:7404
	s_waitcnt lgkmcnt(0)
	ds_read2_b32 v[80:81], v15 offset0:0 offset1:33
	ds_read2_b32 v[82:83], v15 offset0:66 offset1:99
	ds_read2_b32 v[84:85], v15 offset0:132 offset1:165
	ds_read2_b32 v[86:87], v15 offset0:198 offset1:231
	ds_read2_b32 v[88:89], v15 offset0:8 offset1:41
	ds_read2_b32 v[90:91], v15 offset0:74 offset1:107
	ds_read2_b32 v[92:93], v15 offset0:140 offset1:173
	ds_read2_b32 v[94:95], v15 offset0:206 offset1:239
	s_waitcnt lgkmcnt(4)
	v_cvt_pk_bf16_f32 v112, v80, v81
	v_cvt_pk_bf16_f32 v113, v82, v83
	v_cvt_pk_bf16_f32 v114, v84, v85
	v_cvt_pk_bf16_f32 v115, v86, v87
	global_store_dwordx4 v4, v[112:115], s[16:17]
	s_waitcnt lgkmcnt(0)
	v_cvt_pk_bf16_f32 v116, v88, v89
	v_cvt_pk_bf16_f32 v117, v90, v91
	v_cvt_pk_bf16_f32 v118, v92, v93
	v_cvt_pk_bf16_f32 v119, v94, v95
	global_store_dwordx4 v5, v[116:119], s[16:17]
	ds_read2_b32 v[96:97], v15 offset0:16 offset1:49
	ds_read2_b32 v[98:99], v15 offset0:82 offset1:115
	ds_read2_b32 v[100:101], v15 offset0:148 offset1:181
	ds_read2_b32 v[102:103], v15 offset0:214 offset1:247
	ds_read2_b32 v[104:105], v15 offset0:24 offset1:57
	ds_read2_b32 v[106:107], v15 offset0:90 offset1:123
	ds_read2_b32 v[108:109], v15 offset0:156 offset1:189
	ds_read2_b32 v[110:111], v15 offset0:222 offset1:255
	s_waitcnt lgkmcnt(4)
	v_cvt_pk_bf16_f32 v120, v96, v97
	v_cvt_pk_bf16_f32 v121, v98, v99
	v_cvt_pk_bf16_f32 v122, v100, v101
	v_cvt_pk_bf16_f32 v123, v102, v103
	global_store_dwordx4 v6, v[120:123], s[16:17]
	s_waitcnt lgkmcnt(0)
	v_cvt_pk_bf16_f32 v124, v104, v105
	v_cvt_pk_bf16_f32 v125, v106, v107
	v_cvt_pk_bf16_f32 v126, v108, v109
	v_cvt_pk_bf16_f32 v127, v110, v111
	global_store_dwordx4 v7, v[124:127], s[16:17]
	s_add_i32 s44, s44, s8
	s_branch .Lw1_item
